# down-GEMM epilogue counted waits: the 8 gate loads issued together at the top, per-group waits no longer drain the previous group's stores
# speedup vs baseline: 1.0144x; 1.0052x over previous
.LBB0_1331:
	s_lshl_b32 s4, s47, 8
	v_mov_b32_e32 v8, v174
	s_add_i32 s4, s4, s91
	v_mov_b32_e32 v4, v165
	v_and_or_b32 v2, v8, 15, s4
	v_lshlrev_b32_e32 v238, 2, v2
	global_load_dword v230, v238, s[8:9]
	global_load_dword v231, v238, s[8:9] offset:64
	global_load_dword v232, v238, s[8:9] offset:128
	global_load_dword v233, v238, s[8:9] offset:192
	global_load_dword v234, v238, s[8:9] offset:512
	global_load_dword v235, v238, s[8:9] offset:576
	global_load_dword v236, v238, s[8:9] offset:640
	global_load_dword v237, v238, s[8:9] offset:704
	v_ashrrev_i32_e32 v3, 31, v2
	v_lshl_add_u64 v[0:1], v[2:3], 2, s[8:9]
	v_mov_b32_e32 v5, v165
	v_mov_b32_e32 v6, v165
	v_mov_b32_e32 v7, v165
	s_lshl_b32 s16, s46, 8
	v_lshlrev_b64 v[10:11], 10, v[2:3]
	s_ashr_i32 s17, s16, 31
	v_ashrrev_i32_e32 v0, 1, v8
	v_lshl_add_u64 v[10:11], s[88:89], 0, v[10:11]
	v_and_b32_e32 v0, -8, v0
	v_lshl_add_u64 v[10:11], v[10:11], 0, s[16:17]
	v_or_b32_e32 v8, 16, v2
	v_ashrrev_i32_e32 v1, 31, v0
	v_lshl_add_u64 v[10:11], v[10:11], 0, s[68:69]
	v_ashrrev_i32_e32 v9, 31, v8
	v_lshl_add_u64 v[10:11], v[10:11], 0, v[0:1]
	v_lshl_add_u64 v[12:13], v[8:9], 2, s[8:9]
	v_lshlrev_b64 v[8:9], 10, v[8:9]
	v_lshl_add_u64 v[8:9], s[88:89], 0, v[8:9]
	v_lshl_add_u64 v[8:9], v[8:9], 0, s[16:17]
	v_lshl_add_u64 v[8:9], v[8:9], 0, s[68:69]
	v_lshl_add_u64 v[8:9], v[8:9], 0, v[0:1]
	s_and_b64 vcc, exec, s[0:1]
	s_mov_b64 s[0:1], -1
	s_waitcnt vmcnt(7)
	v_mul_f32_e32 v14, 0x3e800000, v230
	v_pk_mul_f32 v[18:19], v[156:157], v[14:15] op_sel_hi:[1,0]
	v_pk_mul_f32 v[22:23], v[152:153], v[14:15] op_sel_hi:[1,0]
	v_pk_mul_f32 v[16:17], v[158:159], v[14:15] op_sel_hi:[1,0]
	v_pk_mul_f32 v[20:21], v[154:155], v[14:15] op_sel_hi:[1,0]
	v_pk_mul_f32 v[24:25], v[150:151], v[14:15] op_sel_hi:[1,0]
	v_pk_mul_f32 v[26:27], v[148:149], v[14:15] op_sel_hi:[1,0]
	v_pk_mul_f32 v[28:29], v[146:147], v[14:15] op_sel_hi:[1,0]
	v_pk_mul_f32 v[14:15], v[144:145], v[14:15] op_sel_hi:[1,0]
	v_cvt_pk_fp8_f32 v4, v18, v19
	v_cvt_pk_fp8_f32 v5, v22, v23
	v_cvt_pk_fp8_f32 v6, v26, v27
	v_cvt_pk_fp8_f32 v7, v14, v15
	v_cvt_pk_fp8_f32 v4, v16, v17 op_sel:[0,0,1]
	v_cvt_pk_fp8_f32 v5, v20, v21 op_sel:[0,0,1]
	v_cvt_pk_fp8_f32 v6, v24, v25 op_sel:[0,0,1]
	v_cvt_pk_fp8_f32 v7, v28, v29 op_sel:[0,0,1]
	global_store_dwordx2 v[10:11], v[4:5], off
	global_store_dwordx2 v[10:11], v[6:7], off offset:128
	v_mov_b32_e32 v4, v165
	v_mov_b32_e32 v5, v165
	v_mov_b32_e32 v6, v165
	v_mov_b32_e32 v7, v165
	v_or_b32_e32 v10, 32, v2
	v_ashrrev_i32_e32 v11, 31, v10
	v_lshl_add_u64 v[12:13], v[10:11], 2, s[8:9]
	v_lshlrev_b64 v[10:11], 10, v[10:11]
	v_lshl_add_u64 v[10:11], s[88:89], 0, v[10:11]
	v_lshl_add_u64 v[10:11], v[10:11], 0, s[16:17]
	v_lshl_add_u64 v[10:11], v[10:11], 0, s[68:69]
	v_lshl_add_u64 v[10:11], v[10:11], 0, v[0:1]
	s_waitcnt vmcnt(8)
	v_mul_f32_e32 v14, 0x3e800000, v231
	v_pk_mul_f32 v[18:19], v[140:141], v[14:15] op_sel_hi:[1,0]
	v_pk_mul_f32 v[22:23], v[136:137], v[14:15] op_sel_hi:[1,0]
	v_pk_mul_f32 v[16:17], v[142:143], v[14:15] op_sel_hi:[1,0]
	v_pk_mul_f32 v[20:21], v[138:139], v[14:15] op_sel_hi:[1,0]
	v_pk_mul_f32 v[24:25], v[134:135], v[14:15] op_sel_hi:[1,0]
	v_pk_mul_f32 v[26:27], v[132:133], v[14:15] op_sel_hi:[1,0]
	v_pk_mul_f32 v[28:29], v[130:131], v[14:15] op_sel_hi:[1,0]
	v_pk_mul_f32 v[14:15], v[128:129], v[14:15] op_sel_hi:[1,0]
	v_cvt_pk_fp8_f32 v4, v18, v19
	v_cvt_pk_fp8_f32 v5, v22, v23
	v_cvt_pk_fp8_f32 v6, v26, v27
	v_cvt_pk_fp8_f32 v7, v14, v15
	v_cvt_pk_fp8_f32 v4, v16, v17 op_sel:[0,0,1]
	v_cvt_pk_fp8_f32 v5, v20, v21 op_sel:[0,0,1]
	v_cvt_pk_fp8_f32 v6, v24, v25 op_sel:[0,0,1]
	v_cvt_pk_fp8_f32 v7, v28, v29 op_sel:[0,0,1]
	global_store_dwordx2 v[8:9], v[4:5], off
	global_store_dwordx2 v[8:9], v[6:7], off offset:128
	v_mov_b32_e32 v4, v165
	v_mov_b32_e32 v5, v165
	v_mov_b32_e32 v6, v165
	v_mov_b32_e32 v7, v165
	v_or_b32_e32 v8, 48, v2
	v_ashrrev_i32_e32 v9, 31, v8
	v_lshl_add_u64 v[12:13], v[8:9], 2, s[8:9]
	v_lshlrev_b64 v[8:9], 10, v[8:9]
	v_lshl_add_u64 v[8:9], s[88:89], 0, v[8:9]
	v_lshl_add_u64 v[8:9], v[8:9], 0, s[16:17]
	v_lshl_add_u64 v[8:9], v[8:9], 0, s[68:69]
	v_lshl_add_u64 v[8:9], v[8:9], 0, v[0:1]
	s_waitcnt vmcnt(9)
	v_mul_f32_e32 v14, 0x3e800000, v232
	v_pk_mul_f32 v[18:19], v[124:125], v[14:15] op_sel_hi:[1,0]
	v_pk_mul_f32 v[22:23], v[120:121], v[14:15] op_sel_hi:[1,0]
	v_pk_mul_f32 v[16:17], v[126:127], v[14:15] op_sel_hi:[1,0]
	v_pk_mul_f32 v[20:21], v[122:123], v[14:15] op_sel_hi:[1,0]
	v_pk_mul_f32 v[24:25], v[118:119], v[14:15] op_sel_hi:[1,0]
	v_pk_mul_f32 v[26:27], v[116:117], v[14:15] op_sel_hi:[1,0]
	v_pk_mul_f32 v[28:29], v[114:115], v[14:15] op_sel_hi:[1,0]
	v_pk_mul_f32 v[14:15], v[112:113], v[14:15] op_sel_hi:[1,0]
	v_cvt_pk_fp8_f32 v4, v18, v19
	v_cvt_pk_fp8_f32 v5, v22, v23
	v_cvt_pk_fp8_f32 v6, v26, v27
	v_cvt_pk_fp8_f32 v7, v14, v15
	v_cvt_pk_fp8_f32 v4, v16, v17 op_sel:[0,0,1]
	v_cvt_pk_fp8_f32 v5, v20, v21 op_sel:[0,0,1]
	v_cvt_pk_fp8_f32 v6, v24, v25 op_sel:[0,0,1]
	v_cvt_pk_fp8_f32 v7, v28, v29 op_sel:[0,0,1]
	global_store_dwordx2 v[10:11], v[4:5], off
	global_store_dwordx2 v[10:11], v[6:7], off offset:128
	v_mov_b32_e32 v4, v165
	v_mov_b32_e32 v5, v165
	v_mov_b32_e32 v6, v165
	v_mov_b32_e32 v7, v165
	v_add_u32_e32 v10, 0x80, v2
	v_ashrrev_i32_e32 v11, 31, v10
	v_lshl_add_u64 v[12:13], v[10:11], 2, s[8:9]
	v_lshlrev_b64 v[10:11], 10, v[10:11]
	v_lshl_add_u64 v[10:11], s[88:89], 0, v[10:11]
	v_lshl_add_u64 v[10:11], v[10:11], 0, s[16:17]
	v_lshl_add_u64 v[10:11], v[10:11], 0, s[68:69]
	v_lshl_add_u64 v[10:11], v[10:11], 0, v[0:1]
	s_waitcnt vmcnt(10)
	v_mul_f32_e32 v14, 0x3e800000, v233
	v_pk_mul_f32 v[18:19], v[108:109], v[14:15] op_sel_hi:[1,0]
	v_pk_mul_f32 v[22:23], v[104:105], v[14:15] op_sel_hi:[1,0]
	v_pk_mul_f32 v[16:17], v[110:111], v[14:15] op_sel_hi:[1,0]
	v_pk_mul_f32 v[20:21], v[106:107], v[14:15] op_sel_hi:[1,0]
	v_pk_mul_f32 v[24:25], v[102:103], v[14:15] op_sel_hi:[1,0]
	v_pk_mul_f32 v[26:27], v[100:101], v[14:15] op_sel_hi:[1,0]
	v_pk_mul_f32 v[28:29], v[98:99], v[14:15] op_sel_hi:[1,0]
	v_pk_mul_f32 v[14:15], v[96:97], v[14:15] op_sel_hi:[1,0]
	v_cvt_pk_fp8_f32 v4, v18, v19
	v_cvt_pk_fp8_f32 v5, v22, v23
	v_cvt_pk_fp8_f32 v6, v26, v27
	v_cvt_pk_fp8_f32 v7, v14, v15
	v_cvt_pk_fp8_f32 v4, v16, v17 op_sel:[0,0,1]
	v_cvt_pk_fp8_f32 v5, v20, v21 op_sel:[0,0,1]
	v_cvt_pk_fp8_f32 v6, v24, v25 op_sel:[0,0,1]
	v_cvt_pk_fp8_f32 v7, v28, v29 op_sel:[0,0,1]
	global_store_dwordx2 v[8:9], v[4:5], off
	global_store_dwordx2 v[8:9], v[6:7], off offset:128
	v_mov_b32_e32 v4, v165
	v_mov_b32_e32 v5, v165
	v_mov_b32_e32 v6, v165
	v_mov_b32_e32 v7, v165
	v_add_u32_e32 v8, 0x90, v2
	v_ashrrev_i32_e32 v9, 31, v8
	v_lshl_add_u64 v[12:13], v[8:9], 2, s[8:9]
	v_lshlrev_b64 v[8:9], 10, v[8:9]
	v_lshl_add_u64 v[8:9], s[88:89], 0, v[8:9]
	v_lshl_add_u64 v[8:9], v[8:9], 0, s[16:17]
	v_lshl_add_u64 v[8:9], v[8:9], 0, s[68:69]
	v_lshl_add_u64 v[8:9], v[8:9], 0, v[0:1]
	s_waitcnt vmcnt(11)
	v_mul_f32_e32 v14, 0x3e800000, v234
	v_pk_mul_f32 v[18:19], v[92:93], v[14:15] op_sel_hi:[1,0]
	v_pk_mul_f32 v[22:23], v[88:89], v[14:15] op_sel_hi:[1,0]
	v_pk_mul_f32 v[16:17], v[94:95], v[14:15] op_sel_hi:[1,0]
	v_pk_mul_f32 v[20:21], v[90:91], v[14:15] op_sel_hi:[1,0]
	v_pk_mul_f32 v[24:25], v[86:87], v[14:15] op_sel_hi:[1,0]
	v_pk_mul_f32 v[26:27], v[84:85], v[14:15] op_sel_hi:[1,0]
	v_pk_mul_f32 v[28:29], v[82:83], v[14:15] op_sel_hi:[1,0]
	v_pk_mul_f32 v[14:15], v[80:81], v[14:15] op_sel_hi:[1,0]
	v_cvt_pk_fp8_f32 v4, v18, v19
	v_cvt_pk_fp8_f32 v5, v22, v23
	v_cvt_pk_fp8_f32 v6, v26, v27
	v_cvt_pk_fp8_f32 v7, v14, v15
	v_cvt_pk_fp8_f32 v4, v16, v17 op_sel:[0,0,1]
	v_cvt_pk_fp8_f32 v5, v20, v21 op_sel:[0,0,1]
	v_cvt_pk_fp8_f32 v6, v24, v25 op_sel:[0,0,1]
	v_cvt_pk_fp8_f32 v7, v28, v29 op_sel:[0,0,1]
	global_store_dwordx2 v[10:11], v[4:5], off
	global_store_dwordx2 v[10:11], v[6:7], off offset:128
	v_mov_b32_e32 v4, v165
	v_mov_b32_e32 v5, v165
	v_mov_b32_e32 v6, v165
	v_mov_b32_e32 v7, v165
	v_add_u32_e32 v10, 0xa0, v2
	v_ashrrev_i32_e32 v11, 31, v10
	v_lshl_add_u64 v[12:13], v[10:11], 2, s[8:9]
	v_add_u32_e32 v2, 0xb0, v2
	s_waitcnt vmcnt(12)
	v_mul_f32_e32 v14, 0x3e800000, v235
	v_pk_mul_f32 v[18:19], v[76:77], v[14:15] op_sel_hi:[1,0]
	v_pk_mul_f32 v[22:23], v[72:73], v[14:15] op_sel_hi:[1,0]
	v_pk_mul_f32 v[16:17], v[78:79], v[14:15] op_sel_hi:[1,0]
	v_pk_mul_f32 v[20:21], v[74:75], v[14:15] op_sel_hi:[1,0]
	v_pk_mul_f32 v[24:25], v[70:71], v[14:15] op_sel_hi:[1,0]
	v_pk_mul_f32 v[26:27], v[68:69], v[14:15] op_sel_hi:[1,0]
	v_pk_mul_f32 v[28:29], v[66:67], v[14:15] op_sel_hi:[1,0]
	v_pk_mul_f32 v[14:15], v[64:65], v[14:15] op_sel_hi:[1,0]
	v_cvt_pk_fp8_f32 v4, v18, v19
	v_cvt_pk_fp8_f32 v5, v22, v23
	v_cvt_pk_fp8_f32 v6, v26, v27
	v_cvt_pk_fp8_f32 v7, v14, v15
	v_cvt_pk_fp8_f32 v4, v16, v17 op_sel:[0,0,1]
	v_cvt_pk_fp8_f32 v5, v20, v21 op_sel:[0,0,1]
	v_cvt_pk_fp8_f32 v6, v24, v25 op_sel:[0,0,1]
	v_cvt_pk_fp8_f32 v7, v28, v29 op_sel:[0,0,1]
	global_store_dwordx2 v[8:9], v[4:5], off
	global_store_dwordx2 v[8:9], v[6:7], off offset:128
	v_mov_b32_e32 v4, v165
	v_mov_b32_e32 v5, v165
	v_mov_b32_e32 v6, v165
	v_mov_b32_e32 v7, v165
	v_lshlrev_b64 v[8:9], 10, v[10:11]
	v_lshl_add_u64 v[8:9], s[88:89], 0, v[8:9]
	v_lshl_add_u64 v[8:9], v[8:9], 0, s[16:17]
	v_lshl_add_u64 v[8:9], v[8:9], 0, s[68:69]
	v_ashrrev_i32_e32 v3, 31, v2
	v_lshl_add_u64 v[8:9], v[8:9], 0, v[0:1]
	v_lshl_add_u64 v[10:11], v[2:3], 2, s[8:9]
	v_lshlrev_b64 v[2:3], 10, v[2:3]
	v_lshl_add_u64 v[2:3], s[88:89], 0, v[2:3]
	v_lshl_add_u64 v[2:3], v[2:3], 0, s[16:17]
	v_lshl_add_u64 v[2:3], v[2:3], 0, s[68:69]
	v_lshl_add_u64 v[0:1], v[2:3], 0, v[0:1]
	s_waitcnt vmcnt(13)
	v_mul_f32_e32 v12, 0x3e800000, v236
	v_pk_mul_f32 v[16:17], v[60:61], v[12:13] op_sel_hi:[1,0]
	v_pk_mul_f32 v[20:21], v[56:57], v[12:13] op_sel_hi:[1,0]
	v_pk_mul_f32 v[14:15], v[62:63], v[12:13] op_sel_hi:[1,0]
	v_pk_mul_f32 v[18:19], v[58:59], v[12:13] op_sel_hi:[1,0]
	v_pk_mul_f32 v[22:23], v[54:55], v[12:13] op_sel_hi:[1,0]
	v_pk_mul_f32 v[24:25], v[52:53], v[12:13] op_sel_hi:[1,0]
	v_pk_mul_f32 v[26:27], v[50:51], v[12:13] op_sel_hi:[1,0]
	v_pk_mul_f32 v[12:13], v[48:49], v[12:13] op_sel_hi:[1,0]
	v_cvt_pk_fp8_f32 v4, v16, v17
	v_cvt_pk_fp8_f32 v5, v20, v21
	v_cvt_pk_fp8_f32 v6, v24, v25
	v_cvt_pk_fp8_f32 v7, v12, v13
	v_cvt_pk_fp8_f32 v4, v14, v15 op_sel:[0,0,1]
	v_cvt_pk_fp8_f32 v5, v18, v19 op_sel:[0,0,1]
	v_cvt_pk_fp8_f32 v6, v22, v23 op_sel:[0,0,1]
	v_cvt_pk_fp8_f32 v7, v26, v27 op_sel:[0,0,1]
	global_store_dwordx2 v[8:9], v[4:5], off
	global_store_dwordx2 v[8:9], v[6:7], off offset:128
	v_mov_b32_e32 v4, v165
	v_mov_b32_e32 v5, v165
	v_mov_b32_e32 v6, v165
	v_mov_b32_e32 v7, v165
	s_waitcnt vmcnt(14)
	v_mul_f32_e32 v8, 0x3e800000, v237
	v_pk_mul_f32 v[12:13], v[44:45], v[8:9] op_sel_hi:[1,0]
	v_pk_mul_f32 v[16:17], v[40:41], v[8:9] op_sel_hi:[1,0]
	v_pk_mul_f32 v[10:11], v[46:47], v[8:9] op_sel_hi:[1,0]
	v_pk_mul_f32 v[14:15], v[42:43], v[8:9] op_sel_hi:[1,0]
	v_pk_mul_f32 v[18:19], v[38:39], v[8:9] op_sel_hi:[1,0]
	v_pk_mul_f32 v[20:21], v[36:37], v[8:9] op_sel_hi:[1,0]
	v_pk_mul_f32 v[22:23], v[34:35], v[8:9] op_sel_hi:[1,0]
	v_pk_mul_f32 v[8:9], v[32:33], v[8:9] op_sel_hi:[1,0]
	v_cvt_pk_fp8_f32 v4, v12, v13
	v_cvt_pk_fp8_f32 v5, v16, v17
	v_cvt_pk_fp8_f32 v6, v20, v21
	v_cvt_pk_fp8_f32 v7, v8, v9
	v_cvt_pk_fp8_f32 v4, v10, v11 op_sel:[0,0,1]
	v_cvt_pk_fp8_f32 v5, v14, v15 op_sel:[0,0,1]
	v_cvt_pk_fp8_f32 v6, v18, v19 op_sel:[0,0,1]
	v_cvt_pk_fp8_f32 v7, v22, v23 op_sel:[0,0,1]
	global_store_dwordx2 v[0:1], v[4:5], off
	global_store_dwordx2 v[0:1], v[6:7], off offset:128
	s_cbranch_vccnz .LBB0_1318
	s_andn2_b64 vcc, exec, s[6:7]
	s_cbranch_vccnz .LBB0_1317
	s_barrier
	s_branch .LBB0_1317
